# baseline (speedup 1.0000x reference)
.LBB0_10:
	s_mov_b64 s[6:7], 0
	s_mov_b64 s[4:5], 0
	s_cmp_gt_i32 s16, 0
	s_cbranch_scc0 .LBB0_19
	s_mov_b32 s6, s21
	s_mov_b32 s6, 8
	s_mov_b32 s6, 16
	s_mov_b32 s6, 24
	s_mov_b32 s6, 32
	s_mov_b32 s6, 40
	s_mov_b32 s6, 48
	s_mov_b32 s6, 56
	s_mov_b32 s6, 64
	s_movk_i32 s6, 0x48
	s_movk_i32 s6, 0x50
	s_movk_i32 s6, 0x58
	s_movk_i32 s6, 0x60
	s_movk_i32 s6, 0x68
	s_movk_i32 s6, 0x70
	s_movk_i32 s6, 0x78
	s_movk_i32 s6, 0x80
	s_movk_i32 s6, 0x88
	s_movk_i32 s6, 0x90
	s_movk_i32 s6, 0x98
	s_movk_i32 s6, 0xa0
	s_movk_i32 s6, 0xa8
	s_movk_i32 s6, 0xb0
	s_movk_i32 s6, 0xb8
	s_movk_i32 s6, 0xc0
	s_movk_i32 s6, 0xc8
	s_movk_i32 s6, 0xd0
	s_movk_i32 s6, 0xd8
	s_movk_i32 s6, 0xe0
	s_movk_i32 s8, 0xe8
	s_mov_b32 s6, -1
	s_waitcnt vmcnt(0)
	v_mbcnt_lo_u32_b32 v0, s6, 0
	v_mbcnt_hi_u32_b32 v0, s6, v0
	v_readlane_b32 s6, v255, 0
	s_nop 1
	v_or_b32_e32 v0, s6, v0
	s_waitcnt vmcnt(0) lgkmcnt(0)
	s_nop 0
	v_cmp_eq_u32_e32 vcc, 0, v0
	s_barrier
	s_and_saveexec_b64 s[6:7], vcc
	s_cbranch_execz .LBB0_18
	s_ashr_i32 s9, s8, 31
	s_add_u32 s8, s0, s8
	v_readlane_b32 s12, v255, 1
	s_addc_u32 s9, s1, s9
	v_readlane_b32 s13, v255, 2
	s_load_dwordx2 s[8:9], s[8:9], 0x0
	s_mov_b64 s[10:11], exec
	s_load_dword s14, s[12:13], 0x0
	buffer_wbl2 sc1
	s_waitcnt lgkmcnt(0)
	s_waitcnt vmcnt(0)
	v_mbcnt_lo_u32_b32 v0, s10, 0
	v_mbcnt_hi_u32_b32 v0, s11, v0
	v_cmp_eq_u32_e32 vcc, 0, v0
	s_and_saveexec_b64 s[12:13], vcc
	s_cbranch_execz .LBB0_15
	s_bcnt1_i32_b64 s10, s[10:11]
	v_mov_b32_e32 v0, s10
	global_atomic_add v163, v0, s[8:9]
.LBB0_15:
	s_or_b64 exec, exec, s[12:13]
	global_load_dword v0, v163, s[8:9] sc1
	s_mul_i32 s14, s14, s16
	s_waitcnt vmcnt(0)
	v_cmp_le_u32_e32 vcc, s14, v0
	s_cbranch_vccnz .LBB0_17

.LBB0_136:
	v_pk_fma_f32 v[170:171], v[0:1], s[62:63], v[138:139] op_sel_hi:[1,0,1]
	v_and_b32_e32 v0, 0x3fffffc0, v40
	s_add_i32 s4, 0, 0x10000
	v_pk_fma_f32 v[140:141], v[14:15], s[62:63], v[138:139] op_sel_hi:[1,0,1]
	v_pk_fma_f32 v[142:143], v[12:13], s[62:63], v[138:139] op_sel_hi:[1,0,1]
	v_pk_fma_f32 v[144:145], v[10:11], s[62:63], v[138:139] op_sel_hi:[1,0,1]
	v_pk_fma_f32 v[154:155], v[8:9], s[62:63], v[138:139] op_sel_hi:[1,0,1]
	v_pk_fma_f32 v[156:157], v[6:7], s[62:63], v[138:139] op_sel_hi:[1,0,1]
	v_pk_fma_f32 v[158:159], v[4:5], s[62:63], v[138:139] op_sel_hi:[1,0,1]
	v_pk_fma_f32 v[160:161], v[2:3], s[62:63], v[138:139] op_sel_hi:[1,0,1]
	v_lshl_add_u32 v198, v0, 2, s4
	s_andn2_b64 vcc, exec, s[6:7]
	v_cmp_eq_u32_e64 s[6:7], 0, v193
	s_cbranch_vccnz .LBB0_158
	v_or_b32_e32 v0, v197, v165
	v_or_b32_e32 v1, v196, v165
	v_or_b32_e32 v2, v195, v165
	v_or_b32_e32 v3, v194, v165
	v_mov_b32_e32 v48, 0
	s_mov_b32 s13, 4
	v_lshlrev_b32_e32 v199, 4, v16
	v_lshlrev_b32_e32 v200, 4, v17
	v_add_u32_e32 v210, 0, v207
	v_lshl_add_u32 v211, v113, 2, v198
	v_lshlrev_b32_e32 v212, 4, v193
	v_mov_b32_e32 v221, 1.0
	v_add_u32_e32 v213, 0, v0
	v_add_u32_e32 v214, 0, v1
	v_add_u32_e32 v215, 0, v2
	v_add_u32_e32 v216, 0, v3
	v_mov_b32_e32 v49, v48
	v_mov_b32_e32 v50, v48
	v_mov_b32_e32 v51, v48
	v_mov_b32_e32 v52, v48
	v_mov_b32_e32 v53, v48
	v_mov_b32_e32 v54, v48
	v_mov_b32_e32 v55, v48
	v_mov_b32_e32 v56, v48
	v_mov_b32_e32 v57, v48
	v_mov_b32_e32 v58, v48
	v_mov_b32_e32 v59, v48
	v_mov_b32_e32 v60, v48
	v_mov_b32_e32 v61, v48
	v_mov_b32_e32 v62, v48
	v_mov_b32_e32 v63, v48
	v_mov_b32_e32 v32, v48
	v_mov_b32_e32 v33, v48
	v_mov_b32_e32 v34, v48
	v_mov_b32_e32 v35, v48
	v_mov_b32_e32 v36, v48
	v_mov_b32_e32 v37, v48
	v_mov_b32_e32 v38, v48
	v_mov_b32_e32 v39, v48
	v_mov_b32_e32 v40, v48
	v_mov_b32_e32 v41, v48
	v_mov_b32_e32 v42, v48
	v_mov_b32_e32 v43, v48
	v_mov_b32_e32 v44, v48
	v_mov_b32_e32 v45, v48
	v_mov_b32_e32 v46, v48
	v_mov_b32_e32 v47, v48
	v_mov_b32_e32 v16, v48
	v_mov_b32_e32 v17, v48
	v_mov_b32_e32 v18, v48
	v_mov_b32_e32 v19, v48
	v_mov_b32_e32 v20, v48
	v_mov_b32_e32 v21, v48
	v_mov_b32_e32 v22, v48
	v_mov_b32_e32 v23, v48
	v_mov_b32_e32 v24, v48
	v_mov_b32_e32 v25, v48
	v_mov_b32_e32 v26, v48
	v_mov_b32_e32 v27, v48
	v_mov_b32_e32 v28, v48
	v_mov_b32_e32 v29, v48
	v_mov_b32_e32 v30, v48
	v_mov_b32_e32 v31, v48
	v_mov_b32_e32 v0, v48
	v_mov_b32_e32 v1, v48
	v_mov_b32_e32 v2, v48
	v_mov_b32_e32 v3, v48
	v_mov_b32_e32 v4, v48
	v_mov_b32_e32 v5, v48
	v_mov_b32_e32 v6, v48
	v_mov_b32_e32 v7, v48
	v_mov_b32_e32 v8, v48
	v_mov_b32_e32 v9, v48
	v_mov_b32_e32 v10, v48
	v_mov_b32_e32 v11, v48
	v_mov_b32_e32 v12, v48
	v_mov_b32_e32 v13, v48
	v_mov_b32_e32 v14, v48
	v_mov_b32_e32 v15, v48
	v_mov_b32_e32 v64, v48
	v_mov_b32_e32 v65, v48
	v_mov_b32_e32 v66, v48
	v_mov_b32_e32 v67, v48
	v_mov_b32_e32 v68, v48
	v_mov_b32_e32 v69, v48
	v_mov_b32_e32 v70, v48
	v_mov_b32_e32 v71, v48
	v_mov_b32_e32 v72, v48
	v_mov_b32_e32 v73, v48
	v_mov_b32_e32 v74, v48
	v_mov_b32_e32 v75, v48
	v_mov_b32_e32 v76, v48
	v_mov_b32_e32 v77, v48
	v_mov_b32_e32 v78, v48
	v_mov_b32_e32 v79, v48
	s_branch .LBB0_138
.Lrot_head_d:
	s_barrier
.LBB0_138:
	ds_read_b128 v[80:83], v213 offset:49152
	ds_read_b128 v[84:87], v214 offset:49152
	ds_read_b128 v[222:225], v202 offset:53248
	ds_read_b128 v[226:229], v203 offset:53248
	ds_read_b128 v[230:233], v215 offset:49152
	ds_read_b128 v[234:237], v216 offset:49152
	ds_read_b128 v[238:241], v204 offset:53248
	ds_read_b128 v[242:245], v205 offset:53248
	s_waitcnt lgkmcnt(6)
	v_mfma_f32_32x32x64_f8f6f4 v[96:111], v[80:87], v[122:129], 0
	s_waitcnt lgkmcnt(4)
	v_mfma_f32_32x32x64_f8f6f4 v[80:95], v[222:229], v[122:129], 0
	s_waitcnt lgkmcnt(2)
	v_mfma_f32_32x32x64_f8f6f4 v[96:111], v[230:237], v[130:137], v[96:111]
	s_waitcnt lgkmcnt(0)
	v_mfma_f32_32x32x64_f8f6f4 v[80:95], v[238:245], v[130:137], v[80:95]
	v_exp_f32_e32 v139, v170
	v_exp_f32_e32 v162, v171
	v_exp_f32_e32 v158, v158
	v_exp_f32_e32 v159, v159
	v_exp_f32_e32 v154, v154
	v_exp_f32_e32 v155, v155
	v_exp_f32_e32 v142, v142
	v_exp_f32_e32 v143, v143
	v_exp_f32_e32 v160, v160
	v_exp_f32_e32 v161, v161
	v_exp_f32_e32 v156, v156
	v_exp_f32_e32 v157, v157
	v_exp_f32_e32 v144, v144
	v_exp_f32_e32 v145, v145
	v_exp_f32_e32 v140, v140
	v_exp_f32_e32 v141, v141
	v_cvt_pk_fp8_f32 v222, v219, v220
	v_cvt_pk_fp8_f32 v226, v139, v162
	v_cvt_pk_fp8_f32 v223, v185, v218
	v_cvt_pk_fp8_f32 v227, v158, v159
	v_cvt_pk_fp8_f32 v224, v180, v182
	v_cvt_pk_fp8_f32 v228, v154, v155
	v_cvt_pk_fp8_f32 v225, v177, v178
	v_cvt_pk_fp8_f32 v229, v142, v143
	v_cvt_pk_fp8_f32 v222, v179, v181 op_sel:[0,0,1]
	v_cvt_pk_fp8_f32 v226, v160, v161 op_sel:[0,0,1]
	v_cvt_pk_fp8_f32 v223, v183, v184 op_sel:[0,0,1]
	v_cvt_pk_fp8_f32 v227, v156, v157 op_sel:[0,0,1]
	v_cvt_pk_fp8_f32 v224, v173, v174 op_sel:[0,0,1]
	v_cvt_pk_fp8_f32 v228, v144, v145 op_sel:[0,0,1]
	v_cvt_pk_fp8_f32 v225, v175, v176 op_sel:[0,0,1]
	v_cvt_pk_fp8_f32 v229, v140, v141 op_sel:[0,0,1]
	s_add_i32 s4, s13, -1
	s_cmp_lt_i32 s4, s11
	s_cselect_b32 s5, 0, s11
	s_cselect_b32 s9, s91, s95
	s_cselect_b32 s8, s90, s94
	s_cselect_b32 s14, s92, s96
	s_cselect_b32 s15, s93, s97
	s_sub_i32 s20, s4, s5
	s_lshl_b64 s[4:5], s[20:21], 15
	s_add_u32 s8, s8, s4
	s_addc_u32 s9, s9, s5
	s_add_u32 s4, s14, s4
	s_addc_u32 s5, s15, s5
	v_lshl_add_u64 v[140:141], s[4:5], 0, v[166:167]
	global_load_dwordx4 v[158:161], v[140:141], off
	v_lshl_add_u64 v[140:141], s[8:9], 0, v[168:169]
	global_load_dwordx4 v[154:157], v[140:141], off
	v_add_u32_e32 v162, v210, v199
	v_add_u32_e32 v218, v210, v200
	ds_read_b128 v[174:177], v162
	ds_read_b128 v[230:233], v162 offset:2048
	ds_read_b128 v[178:181], v218
	ds_read_b128 v[234:237], v218 offset:2048
	ds_read_b128 v[238:241], v162 offset:4096
	ds_read_b128 v[246:249], v162 offset:6144
	ds_read_b128 v[242:245], v218 offset:4096
	ds_read_b128 v[250:253], v218 offset:6144
	s_waitcnt lgkmcnt(5)
	v_mfma_f32_32x32x64_f8f6f4 v[48:63], v[222:229], v[174:181], v[48:63]
	s_waitcnt lgkmcnt(4)
	v_mfma_f32_32x32x64_f8f6f4 v[32:47], v[222:229], v[230:237], v[32:47]
	s_waitcnt lgkmcnt(1)
	v_mfma_f32_32x32x64_f8f6f4 v[16:31], v[222:229], v[238:245], v[16:31]
	s_waitcnt lgkmcnt(0)
	v_mfma_f32_32x32x64_f8f6f4 v[0:15], v[222:229], v[246:253], v[0:15]
	v_mfma_f32_32x32x64_f8f6f4 v[64:79], v[222:229], v[114:121], v[64:79]
	v_max_f32_e32 v139, v97, v97
	v_max_f32_e32 v140, v96, v96
	v_max_f32_e32 v139, v140, v139
	v_max3_f32 v139, v139, v98, v99
	v_max3_f32 v139, v139, v100, v101
	v_max3_f32 v139, v139, v102, v103
	v_max3_f32 v139, v139, v104, v105
	v_max3_f32 v139, v139, v106, v107
	v_max3_f32 v139, v139, v108, v109
	v_max3_f32 v139, v139, v110, v111
	v_max3_f32 v139, v139, v80, v81
	v_max3_f32 v139, v139, v82, v83
	v_max3_f32 v139, v139, v84, v85
	v_max3_f32 v139, v139, v86, v87
	v_max3_f32 v139, v139, v88, v89
	v_max3_f32 v139, v139, v90, v91
	v_max3_f32 v139, v139, v92, v93
	v_max3_f32 v139, v139, v94, v95
	v_mov_b32_e32 v140, v139
	s_nop 1
	v_permlane32_swap_b32_e32 v139, v140
	v_max_f32_e32 v140, v140, v140
	v_max_f32_e32 v139, v139, v139
	v_max_f32_e32 v139, v139, v140
	v_sub_f32_e32 v140, v139, v172
	v_cmp_ge_f32_e32 vcc, s63, v140
	s_cmp_lg_u64 vcc, exec
	s_cselect_b64 s[8:9], -1, 0
	s_mov_b64 vcc, s[8:9]
	s_cbranch_vccnz .LBB0_156
	v_mov_b32_e32 v140, v138

.LBB0_154:
	v_pk_fma_f32 v[96:97], v[96:97], s[62:63], v[162:163] op_sel_hi:[1,0,0]
	v_pk_fma_f32 v[98:99], v[98:99], s[62:63], v[162:163] op_sel_hi:[1,0,0]
	v_pk_fma_f32 v[100:101], v[100:101], s[62:63], v[162:163] op_sel_hi:[1,0,0]
	v_pk_fma_f32 v[102:103], v[102:103], s[62:63], v[162:163] op_sel_hi:[1,0,0]
	v_pk_fma_f32 v[104:105], v[104:105], s[62:63], v[162:163] op_sel_hi:[1,0,0]
	v_pk_fma_f32 v[106:107], v[106:107], s[62:63], v[162:163] op_sel_hi:[1,0,0]
	v_pk_fma_f32 v[108:109], v[108:109], s[62:63], v[162:163] op_sel_hi:[1,0,0]
	v_pk_fma_f32 v[110:111], v[110:111], s[62:63], v[162:163] op_sel_hi:[1,0,0]
	v_exp_f32_e32 v219, v96
	v_exp_f32_e32 v220, v97
	v_exp_f32_e32 v179, v98
	v_exp_f32_e32 v181, v99
	v_exp_f32_e32 v185, v100
	v_exp_f32_e32 v218, v101
	v_exp_f32_e32 v183, v102
	v_exp_f32_e32 v184, v103
	v_exp_f32_e32 v180, v104
	v_exp_f32_e32 v182, v105
	v_exp_f32_e32 v173, v106
	v_exp_f32_e32 v174, v107
	v_exp_f32_e32 v177, v108
	v_exp_f32_e32 v178, v109
	v_exp_f32_e32 v175, v110
	v_exp_f32_e32 v176, v111
	v_pk_fma_f32 v[140:141], v[94:95], s[62:63], v[162:163] op_sel_hi:[1,0,0]
	v_pk_fma_f32 v[142:143], v[92:93], s[62:63], v[162:163] op_sel_hi:[1,0,0]
	v_pk_fma_f32 v[144:145], v[90:91], s[62:63], v[162:163] op_sel_hi:[1,0,0]
	v_pk_fma_f32 v[154:155], v[88:89], s[62:63], v[162:163] op_sel_hi:[1,0,0]
	v_pk_fma_f32 v[156:157], v[86:87], s[62:63], v[162:163] op_sel_hi:[1,0,0]
	v_pk_fma_f32 v[158:159], v[84:85], s[62:63], v[162:163] op_sel_hi:[1,0,0]
	v_pk_fma_f32 v[160:161], v[82:83], s[62:63], v[162:163] op_sel_hi:[1,0,0]
	v_pk_fma_f32 v[170:171], v[80:81], s[62:63], v[162:163] op_sel_hi:[1,0,0]
	s_add_i32 s13, s13, 2
	s_and_b64 vcc, exec, s[4:5]
	s_waitcnt lgkmcnt(0)
	s_cbranch_vccnz .Lrot_exit_d
	v_mov_b32_e32 v221, v209
	v_mov_b32_e32 v217, v139
	s_branch .Lrot_head_d
.Lrot_exit_d:
	s_barrier
	s_branch .LBB0_159

.LBB0_188:
	v_pk_fma_f32 v[178:179], v[0:1], s[62:63], v[166:167] op_sel_hi:[1,0,1]
	v_and_b32_e32 v0, 0x3fffffc0, v40
	s_add_i32 s4, 0, 0x10000
	v_lshl_add_u32 v113, v0, 2, s4
	v_lshrrev_b32_e32 v0, 2, v40
	v_pk_fma_f32 v[154:155], v[14:15], s[62:63], v[166:167] op_sel_hi:[1,0,1]
	v_pk_fma_f32 v[156:157], v[12:13], s[62:63], v[166:167] op_sel_hi:[1,0,1]
	v_pk_fma_f32 v[158:159], v[10:11], s[62:63], v[166:167] op_sel_hi:[1,0,1]
	v_pk_fma_f32 v[160:161], v[8:9], s[62:63], v[166:167] op_sel_hi:[1,0,1]
	v_pk_fma_f32 v[172:173], v[6:7], s[62:63], v[166:167] op_sel_hi:[1,0,1]
	v_pk_fma_f32 v[174:175], v[4:5], s[62:63], v[166:167] op_sel_hi:[1,0,1]
	v_pk_fma_f32 v[176:177], v[2:3], s[62:63], v[166:167] op_sel_hi:[1,0,1]
	s_andn2_b64 vcc, exec, s[6:7]
	v_cmp_eq_u32_e64 s[6:7], 0, v194
	v_lshl_add_u32 v162, v193, 2, v113
	v_bitop3_b32 v200, v41, v0, 3 bitop3:0x78
	v_bitop3_b32 v201, v16, v0, 3 bitop3:0x78
	v_lshl_add_u32 v199, v193, 6, 0
	s_cbranch_vccnz .LBB0_216
	v_or_b32_e32 v0, v198, v192
	v_or_b32_e32 v1, v197, v192
	v_or_b32_e32 v2, v196, v192
	v_or_b32_e32 v3, v195, v192
	v_lshlrev_b32_e32 v4, 4, v200
	v_lshlrev_b32_e32 v5, 4, v201
	s_lshl_b32 s4, s11, 6
	v_mov_b32_e32 v48, 0
	s_mov_b64 s[40:41], s[78:79]
	s_mov_b64 s[78:79], s[72:73]
	s_mov_b64 s[72:73], s[16:17]
	s_mov_b64 s[16:17], s[76:77]
	s_mov_b64 s[76:77], s[70:71]
	s_mov_b64 s[70:71], s[82:83]
	s_mov_b64 s[82:83], s[84:85]
	s_mov_b64 s[84:85], s[80:81]
	s_mov_b64 s[80:81], s[74:75]
	s_mov_b64 s[74:75], s[68:69]
	s_mov_b32 s68, s33
	v_lshl_add_u32 v209, v194, 2, v165
	s_mov_b32 s33, 4
	v_lshlrev_b32_e32 v210, 4, v194
	s_sub_i32 s12, 0, s4
	s_sub_i32 s13, s52, s13
	v_mov_b32_e32 v167, 1.0
	s_xor_b64 s[98:99], s[22:23], -1
	v_add_u32_e32 v211, 0, v0
	v_add_u32_e32 v212, 0, v1
	v_add_u32_e32 v213, 0, v2
	v_add_u32_e32 v214, 0, v3
	v_add_u32_e32 v215, v199, v4
	v_add_u32_e32 v216, v199, v5
	v_mov_b32_e32 v49, v48
	v_mov_b32_e32 v50, v48
	v_mov_b32_e32 v51, v48
	v_mov_b32_e32 v52, v48
	v_mov_b32_e32 v53, v48
	v_mov_b32_e32 v54, v48
	v_mov_b32_e32 v55, v48
	v_mov_b32_e32 v56, v48
	v_mov_b32_e32 v57, v48
	v_mov_b32_e32 v58, v48
	v_mov_b32_e32 v59, v48
	v_mov_b32_e32 v60, v48
	v_mov_b32_e32 v61, v48
	v_mov_b32_e32 v62, v48
	v_mov_b32_e32 v63, v48
	v_mov_b32_e32 v32, v48
	v_mov_b32_e32 v33, v48
	v_mov_b32_e32 v34, v48
	v_mov_b32_e32 v35, v48
	v_mov_b32_e32 v36, v48
	v_mov_b32_e32 v37, v48
	v_mov_b32_e32 v38, v48
	v_mov_b32_e32 v39, v48
	v_mov_b32_e32 v40, v48
	v_mov_b32_e32 v41, v48
	v_mov_b32_e32 v42, v48
	v_mov_b32_e32 v43, v48
	v_mov_b32_e32 v44, v48
	v_mov_b32_e32 v45, v48
	v_mov_b32_e32 v46, v48
	v_mov_b32_e32 v47, v48
	v_mov_b32_e32 v16, v48
	v_mov_b32_e32 v17, v48
	v_mov_b32_e32 v18, v48
	v_mov_b32_e32 v19, v48
	v_mov_b32_e32 v20, v48
	v_mov_b32_e32 v21, v48
	v_mov_b32_e32 v22, v48
	v_mov_b32_e32 v23, v48
	v_mov_b32_e32 v24, v48
	v_mov_b32_e32 v25, v48
	v_mov_b32_e32 v26, v48
	v_mov_b32_e32 v27, v48
	v_mov_b32_e32 v28, v48
	v_mov_b32_e32 v29, v48
	v_mov_b32_e32 v30, v48
	v_mov_b32_e32 v31, v48
	v_mov_b32_e32 v0, v48
	v_mov_b32_e32 v1, v48
	v_mov_b32_e32 v2, v48
	v_mov_b32_e32 v3, v48
	v_mov_b32_e32 v4, v48
	v_mov_b32_e32 v5, v48
	v_mov_b32_e32 v6, v48
	v_mov_b32_e32 v7, v48
	v_mov_b32_e32 v8, v48
	v_mov_b32_e32 v9, v48
	v_mov_b32_e32 v10, v48
	v_mov_b32_e32 v11, v48
	v_mov_b32_e32 v12, v48
	v_mov_b32_e32 v13, v48
	v_mov_b32_e32 v14, v48
	v_mov_b32_e32 v15, v48
	v_mov_b32_e32 v64, v48
	v_mov_b32_e32 v65, v48
	v_mov_b32_e32 v66, v48
	v_mov_b32_e32 v67, v48
	v_mov_b32_e32 v68, v48
	v_mov_b32_e32 v69, v48
	v_mov_b32_e32 v70, v48
	v_mov_b32_e32 v71, v48
	v_mov_b32_e32 v72, v48
	v_mov_b32_e32 v73, v48
	v_mov_b32_e32 v74, v48
	v_mov_b32_e32 v75, v48
	v_mov_b32_e32 v76, v48
	v_mov_b32_e32 v77, v48
	v_mov_b32_e32 v78, v48
	v_mov_b32_e32 v79, v48
	s_branch .LBB0_190
.Lrot_head_w:
	s_barrier
.LBB0_190:
	s_add_i32 s4, s33, -3
	ds_read_b128 v[80:83], v211 offset:49152
	ds_read_b128 v[84:87], v212 offset:49152
	ds_read_b128 v[138:141], v203 offset:53248
	ds_read_b128 v[142:145], v204 offset:53248
	ds_read_b128 v[230:233], v213 offset:49152
	ds_read_b128 v[234:237], v214 offset:49152
	ds_read_b128 v[238:241], v205 offset:53248
	ds_read_b128 v[242:245], v206 offset:53248
	s_waitcnt lgkmcnt(6)
	v_mfma_f32_32x32x64_f8f6f4 v[96:111], v[80:87], v[122:129], 0
	s_waitcnt lgkmcnt(4)
	v_mfma_f32_32x32x64_f8f6f4 v[80:95], v[138:145], v[122:129], 0
	s_waitcnt lgkmcnt(2)
	v_mfma_f32_32x32x64_f8f6f4 v[96:111], v[230:237], v[130:137], v[96:111]
	s_waitcnt lgkmcnt(0)
	v_mfma_f32_32x32x64_f8f6f4 v[80:95], v[238:245], v[130:137], v[80:95]
	s_cmp_lt_i32 s4, s11
	s_cselect_b64 s[4:5], -1, 0
	s_or_b64 s[4:5], s[98:99], s[4:5]
	s_and_b64 vcc, exec, s[4:5]
	s_cbranch_vccnz .LBB0_193
	s_add_i32 s4, s12, s13
	s_add_i32 s4, s4, -2
	s_cmp_gt_u32 s4, 0xffffff5c
	s_cbranch_scc1 .LBB0_193
	v_add_u32_e32 v187, s12, v209
	v_add_u32_e32 v217, 0xffffffbf, v187
	v_cmp_lt_u32_e32 vcc, s67, v217
	v_subrev_u32_e32 v217, 33, v187
	s_nop 0
	v_cndmask_b32_e32 v96, v191, v96, vcc
	v_cmp_lt_u32_e32 vcc, s67, v217
	v_subrev_u32_e32 v217, 64, v187
	s_nop 0
	v_cndmask_b32_e32 v80, v191, v80, vcc
	v_cmp_lt_u32_e32 vcc, s67, v217
	v_subrev_u32_e32 v217, 32, v187
	s_nop 0
	v_cndmask_b32_e32 v97, v191, v97, vcc
	v_cmp_lt_u32_e32 vcc, s67, v217
	v_subrev_u32_e32 v217, 63, v187
	s_nop 0
	v_cndmask_b32_e32 v81, v191, v81, vcc
	v_cmp_lt_u32_e32 vcc, s67, v217
	v_subrev_u32_e32 v217, 31, v187
	s_nop 0
	v_cndmask_b32_e32 v98, v191, v98, vcc
	v_cmp_lt_u32_e32 vcc, s67, v217
	v_subrev_u32_e32 v217, 62, v187
	s_nop 0
	v_cndmask_b32_e32 v82, v191, v82, vcc
	v_cmp_lt_u32_e32 vcc, s67, v217
	v_subrev_u32_e32 v217, 30, v187
	s_nop 0
	v_cndmask_b32_e32 v99, v191, v99, vcc
	v_cmp_lt_u32_e32 vcc, s67, v217
	v_subrev_u32_e32 v217, 57, v187
	s_nop 0
	v_cndmask_b32_e32 v83, v191, v83, vcc
	v_cmp_lt_u32_e32 vcc, s67, v217
	v_subrev_u32_e32 v217, 25, v187
	s_nop 0
	v_cndmask_b32_e32 v100, v191, v100, vcc
	v_cmp_lt_u32_e32 vcc, s67, v217
	v_subrev_u32_e32 v217, 56, v187
	s_nop 0
	v_cndmask_b32_e32 v84, v191, v84, vcc
	v_cmp_lt_u32_e32 vcc, s67, v217
	v_subrev_u32_e32 v217, 24, v187
	s_nop 0
	v_cndmask_b32_e32 v101, v191, v101, vcc
	v_cmp_lt_u32_e32 vcc, s67, v217
	v_subrev_u32_e32 v217, 55, v187
	s_nop 0
	v_cndmask_b32_e32 v85, v191, v85, vcc
	v_cmp_lt_u32_e32 vcc, s67, v217
	v_subrev_u32_e32 v217, 23, v187
	s_nop 0
	v_cndmask_b32_e32 v102, v191, v102, vcc
	v_cmp_lt_u32_e32 vcc, s67, v217
	v_subrev_u32_e32 v217, 54, v187
	s_nop 0
	v_cndmask_b32_e32 v86, v191, v86, vcc
	v_cmp_lt_u32_e32 vcc, s67, v217
	v_subrev_u32_e32 v217, 22, v187
	s_nop 0
	v_cndmask_b32_e32 v103, v191, v103, vcc
	v_cmp_lt_u32_e32 vcc, s67, v217
	v_subrev_u32_e32 v217, 49, v187
	s_nop 0
	v_cndmask_b32_e32 v87, v191, v87, vcc
	v_cmp_lt_u32_e32 vcc, s67, v217
	v_subrev_u32_e32 v217, 17, v187
	s_nop 0
	v_cndmask_b32_e32 v104, v191, v104, vcc
	v_cmp_lt_u32_e32 vcc, s67, v217
	v_subrev_u32_e32 v217, 48, v187
	s_nop 0
	v_cndmask_b32_e32 v88, v191, v88, vcc
	v_cmp_lt_u32_e32 vcc, s67, v217
	v_add_u32_e32 v217, -16, v187
	s_nop 0
	v_cndmask_b32_e32 v105, v191, v105, vcc
	v_cmp_lt_u32_e32 vcc, s67, v217
	v_subrev_u32_e32 v217, 47, v187
	s_nop 0
	v_cndmask_b32_e32 v89, v191, v89, vcc
	v_cmp_lt_u32_e32 vcc, s67, v217
	v_add_u32_e32 v217, -15, v187
	s_nop 0
	v_cndmask_b32_e32 v106, v191, v106, vcc
	v_cmp_lt_u32_e32 vcc, s67, v217
	v_subrev_u32_e32 v217, 46, v187
	s_nop 0
	v_cndmask_b32_e32 v90, v191, v90, vcc
	v_cmp_lt_u32_e32 vcc, s67, v217
	v_add_u32_e32 v217, -14, v187
	s_nop 0
	v_cndmask_b32_e32 v107, v191, v107, vcc
	v_cmp_lt_u32_e32 vcc, s67, v217
	v_subrev_u32_e32 v217, 41, v187
	s_nop 0
	v_cndmask_b32_e32 v91, v191, v91, vcc
	v_cmp_lt_u32_e32 vcc, s67, v217
	v_add_u32_e32 v217, -9, v187
	s_nop 0
	v_cndmask_b32_e32 v108, v191, v108, vcc
	v_cmp_lt_u32_e32 vcc, s67, v217
	v_subrev_u32_e32 v217, 40, v187
	s_nop 0
	v_cndmask_b32_e32 v92, v191, v92, vcc
	v_cmp_lt_u32_e32 vcc, s67, v217
	v_add_u32_e32 v217, -8, v187
	s_nop 0
	v_cndmask_b32_e32 v109, v191, v109, vcc
	v_cmp_lt_u32_e32 vcc, s67, v217
	v_subrev_u32_e32 v217, 39, v187
	s_nop 0
	v_cndmask_b32_e32 v93, v191, v93, vcc
	v_cmp_lt_u32_e32 vcc, s67, v217
	v_add_u32_e32 v217, -7, v187
	s_nop 0
	v_cndmask_b32_e32 v110, v191, v110, vcc
	v_cmp_lt_u32_e32 vcc, s67, v217
	v_subrev_u32_e32 v217, 38, v187
	v_add_u32_e32 v187, -6, v187
	v_cndmask_b32_e32 v94, v191, v94, vcc
	v_cmp_lt_u32_e32 vcc, s67, v217
	s_nop 1
	v_cndmask_b32_e32 v111, v191, v111, vcc
	v_cmp_lt_u32_e32 vcc, s67, v187
	s_nop 1
	v_cndmask_b32_e32 v95, v191, v95, vcc

.LBB0_212:
	v_pk_fma_f32 v[96:97], v[96:97], s[62:63], v[138:139] op_sel_hi:[1,0,0]
	v_pk_fma_f32 v[98:99], v[98:99], s[62:63], v[138:139] op_sel_hi:[1,0,0]
	v_pk_fma_f32 v[100:101], v[100:101], s[62:63], v[138:139] op_sel_hi:[1,0,0]
	v_pk_fma_f32 v[102:103], v[102:103], s[62:63], v[138:139] op_sel_hi:[1,0,0]
	v_pk_fma_f32 v[104:105], v[104:105], s[62:63], v[138:139] op_sel_hi:[1,0,0]
	v_pk_fma_f32 v[106:107], v[106:107], s[62:63], v[138:139] op_sel_hi:[1,0,0]
	v_pk_fma_f32 v[108:109], v[108:109], s[62:63], v[138:139] op_sel_hi:[1,0,0]
	v_pk_fma_f32 v[110:111], v[110:111], s[62:63], v[138:139] op_sel_hi:[1,0,0]
	v_exp_f32_e32 v228, v96
	v_exp_f32_e32 v229, v97
	v_exp_f32_e32 v221, v98
	v_exp_f32_e32 v223, v99
	v_exp_f32_e32 v226, v100
	v_exp_f32_e32 v227, v101
	v_exp_f32_e32 v224, v102
	v_exp_f32_e32 v225, v103
	v_exp_f32_e32 v220, v104
	v_exp_f32_e32 v222, v105
	v_exp_f32_e32 v181, v106
	v_exp_f32_e32 v182, v107
	v_exp_f32_e32 v185, v108
	v_exp_f32_e32 v219, v109
	v_exp_f32_e32 v183, v110
	v_exp_f32_e32 v184, v111
	v_pk_fma_f32 v[154:155], v[94:95], s[62:63], v[138:139] op_sel_hi:[1,0,0]
	v_pk_fma_f32 v[156:157], v[92:93], s[62:63], v[138:139] op_sel_hi:[1,0,0]
	v_pk_fma_f32 v[158:159], v[90:91], s[62:63], v[138:139] op_sel_hi:[1,0,0]
	v_pk_fma_f32 v[160:161], v[88:89], s[62:63], v[138:139] op_sel_hi:[1,0,0]
	v_pk_fma_f32 v[172:173], v[86:87], s[62:63], v[138:139] op_sel_hi:[1,0,0]
	v_pk_fma_f32 v[174:175], v[84:85], s[62:63], v[138:139] op_sel_hi:[1,0,0]
	v_pk_fma_f32 v[176:177], v[82:83], s[62:63], v[138:139] op_sel_hi:[1,0,0]
	v_pk_fma_f32 v[178:179], v[80:81], s[62:63], v[138:139] op_sel_hi:[1,0,0]
	v_add_u32_e32 v209, 0x80, v209
	s_addk_i32 s13, 0x80
	s_add_i32 s33, s33, 2
	s_and_b64 vcc, exec, s[4:5]
	s_waitcnt lgkmcnt(0)
	s_cbranch_vccnz .Lrot_exit_w
	v_mov_b32_e32 v167, v217
	v_mov_b32_e32 v218, v139
	s_branch .Lrot_head_w

.LBB0_369:
	v_mul_f32_e32 v187, v221, v221
	v_fmac_f32_e32 v187, v222, v222
	v_mul_f32_e32 v0, v225, v225
	v_mul_f32_e32 v162, v223, v223
	v_add_f32_dpp v187, v187, v187 quad_perm:[1,0,3,2] row_mask:0xf bank_mask:0xf bound_ctrl:1
	v_fmac_f32_e32 v0, v226, v226
	v_fmac_f32_e32 v162, v224, v224
	v_add_f32_dpp v187, v187, v187 quad_perm:[2,3,0,1] row_mask:0xf bank_mask:0xf bound_ctrl:1
	v_add_f32_dpp v0, v0, v0 quad_perm:[1,0,3,2] row_mask:0xf bank_mask:0xf bound_ctrl:1
	v_add_f32_dpp v162, v162, v162 quad_perm:[1,0,3,2] row_mask:0xf bank_mask:0xf bound_ctrl:1
	v_add_f32_dpp v228, v187, v187 row_half_mirror row_mask:0xf bank_mask:0xf bound_ctrl:1
	v_mul_f32_e32 v187, v219, v219
	v_fmac_f32_e32 v187, v220, v220
	v_add_f32_dpp v0, v0, v0 quad_perm:[2,3,0,1] row_mask:0xf bank_mask:0xf bound_ctrl:1
	v_add_f32_dpp v162, v162, v162 quad_perm:[2,3,0,1] row_mask:0xf bank_mask:0xf bound_ctrl:1
	v_add_f32_dpp v187, v187, v187 quad_perm:[1,0,3,2] row_mask:0xf bank_mask:0xf bound_ctrl:1
	v_add_f32_dpp v0, v0, v0 row_half_mirror row_mask:0xf bank_mask:0xf bound_ctrl:1
	v_add_f32_dpp v162, v162, v162 row_half_mirror row_mask:0xf bank_mask:0xf bound_ctrl:1
	v_add_f32_dpp v187, v187, v187 quad_perm:[2,3,0,1] row_mask:0xf bank_mask:0xf bound_ctrl:1
	v_mov_b32_dpp v1, v0 row_mirror row_mask:0xf bank_mask:0xf bound_ctrl:1
	v_mov_b32_dpp v227, v162 row_mirror row_mask:0xf bank_mask:0xf bound_ctrl:1
	v_add_f32_dpp v230, v187, v187 row_half_mirror row_mask:0xf bank_mask:0xf bound_ctrl:1
	v_mul_f32_e32 v232, v217, v217
	v_mul_f32_e32 v234, v215, v215
	v_mul_f32_e32 v236, v213, v213
	v_mov_b32_dpp v229, v228 row_mirror row_mask:0xf bank_mask:0xf bound_ctrl:1
	v_mov_b32_dpp v231, v230 row_mirror row_mask:0xf bank_mask:0xf bound_ctrl:1
	v_fmac_f32_e32 v232, v218, v218
	v_fmac_f32_e32 v234, v216, v216
	v_fmac_f32_e32 v236, v214, v214
	v_add_f32_dpp v232, v232, v232 quad_perm:[1,0,3,2] row_mask:0xf bank_mask:0xf bound_ctrl:1
	v_add_f32_dpp v234, v234, v234 quad_perm:[1,0,3,2] row_mask:0xf bank_mask:0xf bound_ctrl:1
	v_add_f32_dpp v236, v236, v236 quad_perm:[1,0,3,2] row_mask:0xf bank_mask:0xf bound_ctrl:1
	v_add_f32_dpp v232, v232, v232 quad_perm:[2,3,0,1] row_mask:0xf bank_mask:0xf bound_ctrl:1
	v_add_f32_dpp v234, v234, v234 quad_perm:[2,3,0,1] row_mask:0xf bank_mask:0xf bound_ctrl:1
	v_add_f32_dpp v236, v236, v236 quad_perm:[2,3,0,1] row_mask:0xf bank_mask:0xf bound_ctrl:1
	v_add_f32_dpp v232, v232, v232 row_half_mirror row_mask:0xf bank_mask:0xf bound_ctrl:1
	v_add_f32_dpp v234, v234, v234 row_half_mirror row_mask:0xf bank_mask:0xf bound_ctrl:1
	v_add_f32_dpp v236, v236, v236 row_half_mirror row_mask:0xf bank_mask:0xf bound_ctrl:1
	v_mov_b32_dpp v233, v232 row_mirror row_mask:0xf bank_mask:0xf bound_ctrl:1
	v_mov_b32_dpp v235, v234 row_mirror row_mask:0xf bank_mask:0xf bound_ctrl:1
	v_mov_b32_dpp v237, v236 row_mirror row_mask:0xf bank_mask:0xf bound_ctrl:1
	v_mul_f32_e32 v238, v211, v211
	v_mul_f32_e32 v240, v209, v209
	v_mul_f32_e32 v242, v207, v207
	v_fmac_f32_e32 v238, v212, v212
	v_fmac_f32_e32 v240, v210, v210
	v_fmac_f32_e32 v242, v208, v208
	v_add_f32_dpp v238, v238, v238 quad_perm:[1,0,3,2] row_mask:0xf bank_mask:0xf bound_ctrl:1
	v_add_f32_dpp v240, v240, v240 quad_perm:[1,0,3,2] row_mask:0xf bank_mask:0xf bound_ctrl:1
	v_add_f32_dpp v242, v242, v242 quad_perm:[1,0,3,2] row_mask:0xf bank_mask:0xf bound_ctrl:1
	v_add_f32_dpp v238, v238, v238 quad_perm:[2,3,0,1] row_mask:0xf bank_mask:0xf bound_ctrl:1
	v_add_f32_dpp v240, v240, v240 quad_perm:[2,3,0,1] row_mask:0xf bank_mask:0xf bound_ctrl:1
	v_add_f32_dpp v242, v242, v242 quad_perm:[2,3,0,1] row_mask:0xf bank_mask:0xf bound_ctrl:1
	v_add_f32_dpp v238, v238, v238 row_half_mirror row_mask:0xf bank_mask:0xf bound_ctrl:1
	v_add_f32_dpp v240, v240, v240 row_half_mirror row_mask:0xf bank_mask:0xf bound_ctrl:1
	v_add_f32_dpp v242, v242, v242 row_half_mirror row_mask:0xf bank_mask:0xf bound_ctrl:1
	v_mov_b32_dpp v239, v238 row_mirror row_mask:0xf bank_mask:0xf bound_ctrl:1
	v_mov_b32_dpp v241, v240 row_mirror row_mask:0xf bank_mask:0xf bound_ctrl:1
	v_mov_b32_dpp v243, v242 row_mirror row_mask:0xf bank_mask:0xf bound_ctrl:1
	v_mul_f32_e32 v244, v205, v205
	v_mul_f32_e32 v246, v203, v203
	v_mul_f32_e32 v248, v12, v12
	v_fmac_f32_e32 v244, v206, v206
	v_fmac_f32_e32 v246, v204, v204
	v_fmac_f32_e32 v248, v13, v13
	v_add_f32_dpp v244, v244, v244 quad_perm:[1,0,3,2] row_mask:0xf bank_mask:0xf bound_ctrl:1
	v_add_f32_dpp v246, v246, v246 quad_perm:[1,0,3,2] row_mask:0xf bank_mask:0xf bound_ctrl:1
	v_add_f32_dpp v248, v248, v248 quad_perm:[1,0,3,2] row_mask:0xf bank_mask:0xf bound_ctrl:1
	v_add_f32_dpp v244, v244, v244 quad_perm:[2,3,0,1] row_mask:0xf bank_mask:0xf bound_ctrl:1
	v_add_f32_dpp v246, v246, v246 quad_perm:[2,3,0,1] row_mask:0xf bank_mask:0xf bound_ctrl:1
	v_add_f32_dpp v248, v248, v248 quad_perm:[2,3,0,1] row_mask:0xf bank_mask:0xf bound_ctrl:1
	v_add_f32_dpp v244, v244, v244 row_half_mirror row_mask:0xf bank_mask:0xf bound_ctrl:1
	v_add_f32_dpp v246, v246, v246 row_half_mirror row_mask:0xf bank_mask:0xf bound_ctrl:1
	v_add_f32_dpp v248, v248, v248 row_half_mirror row_mask:0xf bank_mask:0xf bound_ctrl:1
	v_mov_b32_dpp v245, v244 row_mirror row_mask:0xf bank_mask:0xf bound_ctrl:1
	v_mov_b32_dpp v247, v246 row_mirror row_mask:0xf bank_mask:0xf bound_ctrl:1
	v_mov_b32_dpp v249, v248 row_mirror row_mask:0xf bank_mask:0xf bound_ctrl:1
	v_mul_f32_e32 v250, v7, v7
	v_mul_f32_e32 v252, v4, v4
	v_mul_f32_e32 v254, v2, v2
	v_fmac_f32_e32 v250, v9, v9
	v_fmac_f32_e32 v252, v5, v5
	v_fmac_f32_e32 v254, v3, v3
	v_add_f32_dpp v250, v250, v250 quad_perm:[1,0,3,2] row_mask:0xf bank_mask:0xf bound_ctrl:1
	v_add_f32_dpp v252, v252, v252 quad_perm:[1,0,3,2] row_mask:0xf bank_mask:0xf bound_ctrl:1
	v_add_f32_dpp v254, v254, v254 quad_perm:[1,0,3,2] row_mask:0xf bank_mask:0xf bound_ctrl:1
	v_add_f32_dpp v250, v250, v250 quad_perm:[2,3,0,1] row_mask:0xf bank_mask:0xf bound_ctrl:1
	v_add_f32_dpp v252, v252, v252 quad_perm:[2,3,0,1] row_mask:0xf bank_mask:0xf bound_ctrl:1
	v_add_f32_dpp v254, v254, v254 quad_perm:[2,3,0,1] row_mask:0xf bank_mask:0xf bound_ctrl:1
	v_add_f32_dpp v250, v250, v250 row_half_mirror row_mask:0xf bank_mask:0xf bound_ctrl:1
	v_add_f32_dpp v252, v252, v252 row_half_mirror row_mask:0xf bank_mask:0xf bound_ctrl:1
	v_add_f32_dpp v254, v254, v254 row_half_mirror row_mask:0xf bank_mask:0xf bound_ctrl:1
	v_mov_b32_dpp v251, v250 row_mirror row_mask:0xf bank_mask:0xf bound_ctrl:1
	v_mov_b32_dpp v253, v252 row_mirror row_mask:0xf bank_mask:0xf bound_ctrl:1
	v_mov_b32_dpp v187, v254 row_mirror row_mask:0xf bank_mask:0xf bound_ctrl:1
	s_and_saveexec_b64 s[4:5], s[6:7]
	s_cbranch_execz .LBB0_371
	v_add_f32_e32 v0, v0, v1
	v_add_u32_e32 v1, v15, v18
	v_add_f32_e32 v162, v162, v227
	ds_write_b32 v1, v0
	v_add_u32_e32 v0, v15, v19
	v_add_f32_e32 v228, v228, v229
	ds_write_b32 v0, v162
	v_add_u32_e32 v0, v15, v20
	v_add_f32_e32 v230, v230, v231
	ds_write_b32 v0, v228
	v_add_u32_e32 v0, v15, v21
	v_add_f32_e32 v232, v232, v233
	ds_write_b32 v0, v230
	v_add_u32_e32 v0, v15, v22
	v_add_f32_e32 v234, v234, v235
	ds_write_b32 v0, v232
	v_add_u32_e32 v0, v15, v23
	v_add_f32_e32 v236, v236, v237
	ds_write_b32 v0, v234
	v_add_u32_e32 v0, v15, v154
	v_add_f32_e32 v238, v238, v239
	ds_write_b32 v0, v236
	v_add_u32_e32 v0, v15, v155
	v_add_f32_e32 v240, v240, v241
	ds_write_b32 v0, v238
	v_add_u32_e32 v0, v15, v156
	v_add_f32_e32 v242, v242, v243
	ds_write_b32 v0, v240
	v_add_u32_e32 v0, v15, v157
	v_add_f32_e32 v244, v244, v245
	ds_write_b32 v0, v242
	v_add_u32_e32 v0, v15, v158
	v_add_f32_e32 v246, v246, v247
	ds_write_b32 v0, v244
	v_add_u32_e32 v0, v15, v159
	v_add_f32_e32 v248, v248, v249
	ds_write_b32 v0, v246
	v_add_u32_e32 v0, v15, v160
	v_add_f32_e32 v250, v250, v251
	ds_write_b32 v0, v248
	v_add_u32_e32 v0, v15, v161
	v_add_f32_e32 v252, v252, v253
	ds_write_b32 v0, v250
	v_add_u32_e32 v0, v15, v164
	v_add_f32_e32 v187, v254, v187
	ds_write_b32 v0, v252
	v_add_u32_e32 v0, v15, v165
	ds_write_b32 v0, v187
